# v14 plus XCD-affine team scheduling of prompt attention: 4 workgroups of one XCD stream the same batch-head K/V together, ids generated locally
# baseline (speedup 1.0000x reference)
.LBB0_785:
	s_cmp_lt_i32 s96, 5
	s_cselect_b64 s[4:5], -1, 0
	s_cmp_gt_i32 s97, 4
	s_cselect_b64 s[6:7], -1, 0
	s_and_b64 s[4:5], s[4:5], s[6:7]
	s_andn2_b64 vcc, exec, s[4:5]
	s_cbranch_vccnz .LBB0_1063
	s_lshr_b32 s101, s2, 6
	s_lshl_b32 s101, s101, 5
	s_and_b32 s100, s2, 0x1f
	s_or_b32 s101, s101, s100
	s_bitcmp0_b32 s2, 5
	s_cselect_b32 s100, s101, 0x80
	s_lshr_b32 s98, s2, 6
	s_lshl_b32 s98, s98, 5
	s_and_b32 s99, s2, 31
	s_or_b32 s98, s98, s99
	s_and_b32 s99, s98, 7
	s_lshl_b32 s99, s99, 4
	s_lshr_b32 s101, s98, 3
	s_and_b32 s101, s101, 12
	s_add_i32 s99, s99, s101
	s_lshr_b32 s101, s98, 3
	s_and_b32 s101, s101, 3
	s_lshl_b32 s101, s101, 8
	s_or_b32 s99, s99, s101
	s_lshl_b32 s98, s98, 16
	s_or_b32 s98, s98, s99
	s_bitcmp0_b32 s2, 5
	s_cselect_b32 s101, 9, 0
	s_and_b32 s10, s95, 0xffffffc0
	s_bfe_u32 s8, s95, 0x10006
	s_add_u32 s30, s38, 0x12300000
	s_addc_u32 s31, s39, 0
	s_mov_b32 s5, 0
	s_add_u32 s52, s38, 0x100000
	s_mul_i32 s4, s92, 0x60
	s_addc_u32 s53, s39, 0
	s_lshl_b64 s[4:5], s[4:5], 1
	s_add_u32 s56, s30, s4
	s_addc_u32 s57, s31, s5
	s_ashr_i32 s11, s10, 31
	s_lshr_b32 s5, s95, 7
	s_cmpk_lt_u32 s95, 0x80
	s_cselect_b64 s[58:59], -1, 0
	s_lshl_b32 s14, s5, 13
	s_mul_i32 s9, s92, 0x1200
	s_add_i32 s84, 0, 0x22000
	s_mul_i32 s12, s8, 0x1200
	s_add_i32 s83, 0, 0x22900
	s_lshr_b32 s13, s95, 4
	s_and_b32 s15, s14, 0x7fffc000
	s_lshl_b32 s78, s8, 5
	s_add_i32 s45, s84, s9
	s_lshl_b32 s3, s92, 5
	s_add_i32 s76, s83, s12
	s_add_i32 s77, s15, 0
	s_and_b32 s79, s13, 8
	s_or_b32 s80, s78, 8
	s_or_b32 s81, s78, 16
	s_or_b32 s82, s78, 24
	s_add_i32 s83, s83, s9
	s_add_i32 s84, s84, s12
	s_add_u32 s60, s38, 0x10f00000
	s_addc_u32 s61, s39, 0
	s_add_u32 s54, s38, 0x12000000
	s_addc_u32 s55, s39, 0
	s_lshl_b32 s9, s92, 8
	s_add_i32 s88, s9, 0
	v_mbcnt_hi_u32_b32 v187, -1, v254
	s_add_i32 s85, s77, 0x17400
	s_add_i32 s86, s14, 0
	s_add_i32 s87, s88, 0x24400
	s_add_i32 s88, s88, 0x16000
	s_and_b32 s12, 64, s95
	v_writelane_b32 v255, s90, 6
	v_and_b32_e32 v1, 64, v187
	s_cmp_eq_u32 s8, 0
	v_writelane_b32 v255, s91, 7
	s_mul_i32 s4, s92, 0x250
	v_xor_b32_e32 v0, 32, v187
	v_add_u32_e32 v188, 64, v1
	s_cselect_b64 s[8:9], -1, 0
	s_cmp_lg_u32 s12, 0
	v_cmp_lt_i32_e32 vcc, v0, v188
	v_writelane_b32 v255, s95, 8
	s_cselect_b64 s[62:63], -1, 0
	s_add_i32 s90, s4, 0
	s_mul_i32 s4, s92, 0x410
	v_add_u32_e32 v186, s10, v187
	v_cndmask_b32_e32 v0, v187, v0, vcc
	s_lshl_b32 s5, s5, 8
	v_writelane_b32 v255, s92, 5
	s_add_i32 s92, s4, 0
	s_add_i32 s93, 0, 0x21140
	v_lshlrev_b32_e32 v189, 2, v0
	v_cmp_eq_u32_e64 s[6:7], 0, v186
	s_add_i32 s89, s5, 0
	s_lshl_b64 s[64:65], s[10:11], 2
	s_add_i32 s91, s10, 0x200
	s_addk_i32 s92, 0x4c00
	v_mov_b32_e32 v121, 0
	s_mov_b32 s94, 0x8000
	s_movk_i32 s95, 0x600
	s_movk_i32 s96, 0x7fff
	s_movk_i32 s97, 0x50
	s_movk_i32 s50, 0x4000
	s_movk_i32 s51, 0x2000
	s_movk_i32 s4, 0x6000
	s_mov_b32 s5, 0xa000
	s_mov_b32 s48, 0xc000
	s_mov_b32 s49, 0xe000
	s_mov_b32 s74, 0x41000000
	s_lshl_b64 s[66:67], s[10:11], 1
	s_mov_b64 s[68:69], 0x19700400
	s_mov_b32 s75, 0x19700000
	v_mov_b32_e32 v123, s93
	v_mov_b32_e32 v138, 0xff800000
	s_branch .LBB0_789

.LBB0_868:
	s_and_saveexec_b64 s[8:9], s[6:7]
	s_cbranch_execz .LBB0_872
	s_mov_b64 s[12:13], exec
	v_mbcnt_lo_u32_b32 v0, s12, 0
	v_mbcnt_hi_u32_b32 v0, s13, v0
	v_cmp_eq_u32_e32 vcc, 0, v0
	s_and_saveexec_b64 s[10:11], vcc
	s_cbranch_execz .LBB0_871
	s_bcnt1_i32_b64 s12, s[12:13]
	v_mov_b32_e32 v1, s12
	s_cmpk_lg_u32 s44, 0x100
	s_cbranch_scc1 .Lmy_pq_dyn
	s_cmpk_gt_u32 s101, 8
	s_cbranch_scc1 .Lmy_pq_none
	s_cmpk_eq_u32 s101, 8
	s_cbranch_scc1 .Lmy_pq_meta
	s_lshr_b32 s99, s101, 1
	s_and_b32 s100, s98, 0x7f
	s_add_i32 s99, s99, s100
	s_bfe_u32 s100, s98, 0x20008
	s_bitcmp1_b32 s101, 0
	s_cbranch_scc0 .Lmy_pq_even
	s_sub_i32 s100, 7, s100
.Lmy_pq_even:
	s_lshl_b32 s100, s100, 7
	s_add_i32 s99, s99, s100
	s_branch .Lmy_pq_have
.Lmy_pq_meta:
	s_lshr_b32 s99, s98, 16
	s_cmpk_lt_u32 s99, 8
	s_cbranch_scc0 .Lmy_pq_none
	s_addk_i32 s99, 0x400
	s_branch .Lmy_pq_have

.Lmy_pq_have:
	v_mov_b32_e32 v1, s99
	s_add_i32 s101, s101, 1
	s_branch .LBB0_871
